# bonus term: scan staging reduces the partial over the row's 16 lanes and stores one float per (row, head, direction); readout loads it and drops its own reduce
# speedup vs baseline: 1.0074x; 1.0074x over previous
.LBB0_603:
	s_lshl_b32 s0, s33, 4
	s_and_b32 s28, s0, 0x7c0
	s_waitcnt vmcnt(0)
	v_or_b32_e32 v2, s28, v98
	v_lshlrev_b32_e32 v0, 2, v2
	v_lshl_add_u64 v[4:5], s[70:71], 0, v[0:1]
	flat_load_dwordx4 v[42:45], v[4:5]
	v_lshl_add_u64 v[4:5], s[72:73], 0, v[0:1]
	flat_load_dwordx4 v[46:49], v[4:5]
	s_ashr_i32 s14, s33, 7
	s_cmpk_lt_u32 s33, 0x80
	s_cselect_b64 s[12:13], -1, 0
	s_cmpk_gt_u32 s33, 0x7f
	s_cselect_b64 s[88:89], -1, 0
	v_lshl_add_u64 v[4:5], v[188:189], 0, v[0:1]
	flat_load_dwordx4 v[190:193], v[4:5]
	v_mov_b32_e32 v198, 0x9200000
	v_mov_b32_e32 v199, 0xd200000
	v_cndmask_b32_e64 v198, v198, v199, s[88:89]
	v_lshrrev_b32_e32 v199, 4, v2
	v_add_u32_e32 v198, v198, v199
	v_mov_b32_e32 v199, 0
	v_lshl_add_u64 v[198:199], s[26:27], 0, v[198:199]
	s_and_saveexec_b64 s[4:5], s[8:9]
	s_xor_b64 s[4:5], exec, s[4:5]
	s_lshl_b32 s0, s14, 11
	s_ashr_i32 s1, s0, 31
	s_or_saveexec_b64 s[16:17], s[4:5]
	s_and_b32 s4, s33, 3
	v_mov_b64_e32 v[4:5], s[0:1]
	v_lshlrev_b32_e32 v2, 1, v2
	s_xor_b64 exec, exec, s[16:17]
	s_cbranch_execz .LBB0_615
	v_cndmask_b32_e64 v4, v138, v137, s[12:13]
	v_lshlrev_b32_e32 v6, 13, v4
	v_mov_b32_e32 v7, v1
	v_lshlrev_b32_e32 v12, 14, v4
	v_mov_b32_e32 v13, v1
	s_lshl_b32 s18, s14, 11
	v_lshl_add_u64 v[8:9], s[48:49], 0, v[6:7]
	v_lshl_add_u64 v[12:13], s[60:61], 0, v[12:13]
	s_ashr_i32 s19, s18, 31
	v_lshl_add_u64 v[6:7], s[52:53], 0, v[6:7]
	v_lshl_add_u64 v[8:9], v[8:9], 0, v[0:1]
	v_lshlrev_b32_e32 v10, 12, v4
	v_mov_b32_e32 v11, v1
	v_lshl_add_u64 v[12:13], s[18:19], 2, v[12:13]
	v_lshl_add_u64 v[6:7], s[18:19], 1, v[6:7]
	v_mov_b32_e32 v3, v1
	v_lshl_add_u64 v[12:13], v[12:13], 0, v[0:1]
	global_load_dwordx4 v[34:37], v[8:9], off
	global_load_dwordx4 v[38:41], v[12:13], off
	v_lshl_add_u64 v[6:7], v[6:7], 0, v[2:3]
	v_lshl_add_u64 v[8:9], s[66:67], 0, v[10:11]
	v_lshl_add_u64 v[8:9], v[8:9], 0, v[2:3]
	global_load_dwordx2 v[110:111], v[6:7], off
	global_load_dwordx2 v[112:113], v[8:9], off
	s_and_saveexec_b64 s[0:1], s[10:11]
	s_cbranch_execz .LBB0_608
	v_lshlrev_b32_e32 v4, 11, v4
	v_lshlrev_b32_e32 v4, 1, v4
	v_mov_b32_e32 v5, v1
	v_lshl_add_u64 v[4:5], s[68:69], 0, v[4:5]
	s_lshl_b32 s86, s28, 1
	v_lshl_add_u64 v[4:5], v[4:5], 0, s[86:87]
	s_lshl_b32 s86, s4, 5
	v_lshl_add_u64 v[4:5], v[4:5], 0, s[86:87]
	v_lshlrev_b32_e32 v6, 1, v98
	v_mov_b32_e32 v7, v1
	v_lshl_add_u64 v[4:5], v[4:5], 0, v[6:7]
	global_load_dwordx2 v[106:107], v[4:5], off

.LBB0_728:
	s_or_b64 exec, exec, s[0:1]
	v_cmp_lt_u32_e32 vcc, 7, v64
	s_and_saveexec_b64 s[0:1], vcc
	s_cbranch_execz .Lscan_bonus_a
	v_pk_mul_f32 v[194:195], v[74:75], v[190:191]
	v_pk_mul_f32 v[196:197], v[76:77], v[192:193]
	v_pk_mul_f32 v[194:195], v[194:195], v[66:67]
	v_lshl_add_u32 v200, v64, 5, v131
	v_pk_fma_f32 v[194:195], v[196:197], v[68:69], v[194:195]
	v_sub_u32_e32 v201, 0x20ff, v200
	v_add_u32_e32 v200, 0xffffff00, v200
	v_cndmask_b32_e64 v200, v200, v201, s[88:89]
	v_add_f32_e32 v194, v194, v195
	v_lshlrev_b32_e32 v200, 7, v200
	v_mov_b32_e32 v201, 0
	v_add_f32_dpp v194, v194, v194 quad_perm:[1,0,3,2] row_mask:0xf bank_mask:0xf bound_ctrl:1
	v_lshl_add_u64 v[200:201], v[198:199], 0, v[200:201]
	s_nop 0
	v_add_f32_dpp v194, v194, v194 quad_perm:[2,3,0,1] row_mask:0xf bank_mask:0xf bound_ctrl:1
	s_nop 1
	v_add_f32_dpp v194, v194, v194 row_half_mirror row_mask:0xf bank_mask:0xf bound_ctrl:1
	s_nop 1
	v_add_f32_dpp v194, v194, v194 row_ror:8 row_mask:0xf bank_mask:0xf bound_ctrl:1
	v_cmp_eq_u32_e32 vcc, 0, v98
	s_and_b64 exec, exec, vcc
	global_store_dword v[200:201], v194, off

.Lscan_stage_tail:
	s_or_b64 exec, exec, s[0:1]
	v_cmp_lt_u32_e32 vcc, 7, v64
	s_and_saveexec_b64 s[0:1], vcc
	s_cbranch_execz .Lscan_bonus_b
	v_pk_mul_f32 v[194:195], v[74:75], v[190:191]
	v_pk_mul_f32 v[196:197], v[76:77], v[192:193]
	v_pk_mul_f32 v[194:195], v[194:195], v[66:67]
	v_lshl_add_u32 v200, v64, 5, v136
	v_pk_fma_f32 v[194:195], v[196:197], v[68:69], v[194:195]
	v_sub_u32_e32 v201, 0x20ff, v200
	v_add_u32_e32 v200, 0xffffff00, v200
	v_cndmask_b32_e64 v200, v200, v201, s[88:89]
	v_add_f32_e32 v194, v194, v195
	v_lshlrev_b32_e32 v200, 7, v200
	v_mov_b32_e32 v201, 0
	v_add_f32_dpp v194, v194, v194 quad_perm:[1,0,3,2] row_mask:0xf bank_mask:0xf bound_ctrl:1
	v_lshl_add_u64 v[200:201], v[198:199], 0, v[200:201]
	s_nop 0
	v_add_f32_dpp v194, v194, v194 quad_perm:[2,3,0,1] row_mask:0xf bank_mask:0xf bound_ctrl:1
	s_nop 1
	v_add_f32_dpp v194, v194, v194 row_half_mirror row_mask:0xf bank_mask:0xf bound_ctrl:1
	s_nop 1
	v_add_f32_dpp v194, v194, v194 row_ror:8 row_mask:0xf bank_mask:0xf bound_ctrl:1
	v_cmp_eq_u32_e32 vcc, 0, v98
	s_and_b64 exec, exec, vcc
	global_store_dword v[200:201], v194, off

.LBB0_784:
	s_or_b64 exec, exec, s[6:7]
	v_readlane_b32 s0, v255, 10
	v_readlane_b32 s1, v255, 11
	s_waitcnt lgkmcnt(0)
	v_mov_b32_e32 v0, v254
	s_waitcnt vmcnt(0)
	v_mov_b64_e32 v[2:3], s[0:1]
	s_barrier
	flat_load_dwordx2 v[4:5], v[2:3] offset:200 sc0 sc1
	flat_load_dwordx2 v[6:7], v[2:3] offset:208 sc0 sc1
	flat_load_dwordx2 v[8:9], v[2:3] offset:216 sc0 sc1
	flat_load_dwordx2 v[2:3], v[2:3] offset:224 sc0 sc1
	s_waitcnt vmcnt(0)
	s_add_u32 s8, s26, 0xf200000
	v_readfirstlane_b32 s0, v0
	s_addc_u32 s9, s27, 0
	s_ashr_i32 s0, s0, 6
	v_readlane_b32 s1, v255, 6
	s_add_i32 s20, s0, s1
	s_cmp_lt_i32 s20, 0x10000
	s_waitcnt lgkmcnt(0)
	v_readfirstlane_b32 s11, v5
	v_readfirstlane_b32 s10, v4
	v_readfirstlane_b32 s13, v7
	v_readfirstlane_b32 s12, v6
	v_readfirstlane_b32 s15, v9
	v_readfirstlane_b32 s14, v8
	v_readfirstlane_b32 s17, v3
	v_readfirstlane_b32 s16, v2
	s_cbranch_scc0 .LBB0_787
	s_add_u32 s18, s26, 0xb200000
	s_addc_u32 s19, s27, 0
	v_lshlrev_b32_e32 v0, 2, v0
	s_lshl_b32 s1, s2, 11
	s_lshl_b32 s0, s0, 8
	v_and_b32_e32 v2, 0xfc, v0
	s_add_i32 s21, s1, s0
	s_lshl_b32 s23, s30, 11
	v_mov_b32_e32 v3, 0x3a27c5ac
	s_mov_b32 s24, 0xf800000
	v_mov_b32_e32 v4, 0x260
	v_mov_b32_e32 v1, 0
	s_movk_i32 s25, 0x1000
	s_and_b32 s0, s21, 0x700
	v_or_b32_e32 v124, s0, v2
	v_lshrrev_b32_e32 v125, 6, v124
	v_lshlrev_b32_e32 v125, 2, v125
	v_add_u32_e32 v125, 0x2000000, v125
	v_lshlrev_b32_e32 v120, 2, v124
	global_load_dwordx4 v[60:63], v120, s[14:15]
	global_load_dwordx4 v[64:67], v120, s[16:17]
	s_min_i32 s0, s20, 0xffff
	s_ashr_i32 s0, s0, 3
	s_lshl_b32 s1, s0, 11
	s_lshl_b32 s5, s0, 7
	v_add_u32_e32 v121, s1, v124
	v_lshlrev_b32_e32 v98, 1, v121
	v_add_u32_e32 v121, s5, v125
	global_load_dwordx2 v[80:81], v98, s[38:39]
	global_load_dwordx2 v[82:83], v98, s[18:19]
	global_load_dwordx2 v[86:87], v98, s[68:69]
	global_load_dwordx2 v[88:89], v98, s[56:57]
	global_load_dword v94, v121, s[38:39]
	global_load_dword v95, v121, s[18:19]
	s_add_i32 s20, s20, s22
	s_min_i32 s0, s20, 0xffff
	s_ashr_i32 s0, s0, 3
	s_lshl_b32 s1, s0, 11
	s_lshl_b32 s5, s0, 7
	v_add_u32_e32 v121, s1, v124
	v_lshlrev_b32_e32 v118, 1, v121
	v_add_u32_e32 v121, s5, v125
	global_load_dwordx2 v[100:101], v118, s[38:39]
	global_load_dwordx2 v[102:103], v118, s[18:19]
	global_load_dwordx2 v[106:107], v118, s[68:69]
	global_load_dwordx2 v[108:109], v118, s[56:57]
	global_load_dword v114, v121, s[38:39]
	global_load_dword v115, v121, s[18:19]
	s_add_i32 s20, s20, s22
	s_movk_i32 s4, 16
.Lp6_loop:
	s_waitcnt vmcnt(6)
	v_mov_b64_e32 v[28:29], v[80:81]
	v_mov_b64_e32 v[30:31], v[82:83]
	v_mov_b64_e32 v[34:35], v[86:87]
	v_mov_b64_e32 v[36:37], v[88:89]
	v_mov_b64_e32 v[42:43], v[94:95]
	v_mov_b32_e32 v26, v98
	v_mov_b64_e32 v[6:7], v[60:61]
	v_mov_b64_e32 v[8:9], v[62:63]
	v_mov_b64_e32 v[10:11], v[64:65]
	v_mov_b64_e32 v[12:13], v[66:67]
	s_min_i32 s0, s20, 0xffff
	s_ashr_i32 s0, s0, 3
	s_lshl_b32 s1, s0, 11
	s_lshl_b32 s5, s0, 7
	v_add_u32_e32 v121, s1, v124
	v_lshlrev_b32_e32 v98, 1, v121
	v_add_u32_e32 v121, s5, v125
	global_load_dwordx2 v[80:81], v98, s[38:39]
	global_load_dwordx2 v[82:83], v98, s[18:19]
	global_load_dwordx2 v[86:87], v98, s[68:69]
	global_load_dwordx2 v[88:89], v98, s[56:57]
	global_load_dword v94, v121, s[38:39]
	global_load_dword v95, v121, s[18:19]
	s_add_i32 s20, s20, s22
	v_lshlrev_b32_e32 v44, 16, v28
	v_and_b32_e32 v45, 0xffff0000, v28
	v_lshlrev_b32_e32 v28, 16, v29
	v_and_b32_e32 v29, 0xffff0000, v29
	v_lshlrev_b32_e32 v46, 16, v30
	v_and_b32_e32 v47, 0xffff0000, v30
	v_lshlrev_b32_e32 v30, 16, v31
	v_and_b32_e32 v31, 0xffff0000, v31
	v_pk_add_f32 v[28:29], v[28:29], v[30:31]
	v_pk_add_f32 v[30:31], v[44:45], v[46:47]
	v_add_f32_e32 v0, v30, v31
	v_add_f32_e32 v0, v28, v0
	v_add_f32_e32 v0, v29, v0
	s_nop 1
	v_add_f32_dpp v0, v0, v0 quad_perm:[1,0,3,2] row_mask:0xf bank_mask:0xf bound_ctrl:1
	s_nop 0
	v_add_f32_dpp v0, v0, v0 quad_perm:[2,3,0,1] row_mask:0xf bank_mask:0xf bound_ctrl:1
	s_nop 1
	v_add_f32_dpp v0, v0, v0 row_half_mirror row_mask:0xf bank_mask:0xf bound_ctrl:1
	s_nop 1
	v_add_f32_dpp v0, v0, v0 row_ror:8 row_mask:0xf bank_mask:0xf bound_ctrl:1
	v_fmamk_f32 v31, v0, 0xbc800000, v31
	v_fmac_f32_e32 v30, 0xbc800000, v0
	v_fmamk_f32 v29, v0, 0xbc800000, v29
	v_fmac_f32_e32 v28, 0xbc800000, v0
	v_pk_mul_f32 v[18:19], v[30:31], v[30:31]
	v_pk_mul_f32 v[14:15], v[28:29], v[28:29]
	v_add_f32_e32 v5, v18, v19
	v_add_f32_e32 v5, v14, v5
	v_add_f32_e32 v5, v15, v5
	v_add_f32_e32 v0, v42, v43
	v_lshlrev_b32_e32 v50, 16, v34
	v_add_f32_dpp v5, v5, v5 quad_perm:[1,0,3,2] row_mask:0xf bank_mask:0xf bound_ctrl:1
	s_nop 0
	v_and_b32_e32 v51, 0xffff0000, v34
	v_add_f32_dpp v5, v5, v5 quad_perm:[2,3,0,1] row_mask:0xf bank_mask:0xf bound_ctrl:1
	s_nop 0
	v_lshlrev_b32_e32 v34, 16, v35
	v_add_f32_dpp v5, v5, v5 row_half_mirror row_mask:0xf bank_mask:0xf bound_ctrl:1
	s_nop 0
	v_and_b32_e32 v35, 0xffff0000, v35
	v_add_f32_dpp v5, v5, v5 row_ror:8 row_mask:0xf bank_mask:0xf bound_ctrl:1
	v_fmamk_f32 v5, v5, 0x3c800000, v3
	v_mul_f32_e32 v14, 0x4f800000, v5
	v_cmp_gt_f32_e32 vcc, s24, v5
	s_nop 0
	v_lshlrev_b32_e32 v52, 16, v36
	v_cndmask_b32_e32 v5, v5, v14, vcc
	v_sqrt_f32_e32 v14, v5
	v_and_b32_e32 v53, 0xffff0000, v36
	v_lshlrev_b32_e32 v36, 16, v37
	v_and_b32_e32 v37, 0xffff0000, v37
	v_add_u32_e32 v15, -1, v14
	v_add_u32_e32 v16, 1, v14
	v_fma_f32 v17, -v15, v14, v5
	v_fma_f32 v18, -v16, v14, v5
	v_cmp_ge_f32_e64 s[6:7], 0, v17
	s_nop 1
	v_cndmask_b32_e64 v14, v14, v15, s[6:7]
	v_cmp_lt_f32_e64 s[6:7], 0, v18
	s_nop 1
	v_cndmask_b32_e64 v14, v14, v16, s[6:7]
	v_mul_f32_e32 v15, 0x37800000, v14
	v_cndmask_b32_e32 v14, v14, v15, vcc
	v_cmp_class_f32_e32 vcc, v5, v4
	s_nop 1
	v_cndmask_b32_e32 v5, v14, v5, vcc
	v_div_scale_f32 v14, s[0:1], v5, v5, 1.0
	v_rcp_f32_e32 v16, v14
	v_div_scale_f32 v15, vcc, 1.0, v5, 1.0
	v_fma_f32 v17, -v14, v16, 1.0
	v_fmac_f32_e32 v16, v17, v16
	v_mul_f32_e32 v17, v15, v16
	v_fma_f32 v18, -v14, v17, v15
	v_fmac_f32_e32 v17, v18, v16
	v_fma_f32 v14, -v14, v17, v15
	v_div_fmas_f32 v14, v14, v16, v17
	v_div_fixup_f32 v14, v14, v5, 1.0
	v_pk_mul_f32 v[16:17], v[30:31], v[14:15] op_sel_hi:[1,0]
	v_pk_mul_f32 v[14:15], v[28:29], v[14:15] op_sel_hi:[1,0]
	v_pk_fma_f32 v[6:7], v[6:7], v[16:17], v[10:11]
	v_pk_fma_f32 v[8:9], v[8:9], v[14:15], v[12:13]
	v_pk_fma_f32 v[6:7], v[0:1], v[50:51], v[6:7] op_sel_hi:[0,1,1]
	v_pk_fma_f32 v[8:9], v[0:1], v[34:35], v[8:9] op_sel_hi:[0,1,1]
	v_pk_mul_f32 v[6:7], v[6:7], v[52:53]
	v_pk_mul_f32 v[8:9], v[8:9], v[36:37]
	s_nop 1
	v_cvt_pk_bf16_f32 v6, v6, v7
	s_nop 0
	s_nop 1
	v_cvt_pk_bf16_f32 v7, v8, v9
	global_store_dwordx2 v26, v[6:7], s[8:9]
	s_waitcnt vmcnt(6)
	v_mov_b64_e32 v[28:29], v[100:101]
	v_mov_b64_e32 v[30:31], v[102:103]
	v_mov_b64_e32 v[34:35], v[106:107]
	v_mov_b64_e32 v[36:37], v[108:109]
	v_mov_b64_e32 v[42:43], v[114:115]
	v_mov_b32_e32 v26, v118
	v_mov_b64_e32 v[6:7], v[60:61]
	v_mov_b64_e32 v[8:9], v[62:63]
	v_mov_b64_e32 v[10:11], v[64:65]
	v_mov_b64_e32 v[12:13], v[66:67]
	s_min_i32 s0, s20, 0xffff
	s_ashr_i32 s0, s0, 3
	s_lshl_b32 s1, s0, 11
	s_lshl_b32 s5, s0, 7
	v_add_u32_e32 v121, s1, v124
	v_lshlrev_b32_e32 v118, 1, v121
	v_add_u32_e32 v121, s5, v125
	global_load_dwordx2 v[100:101], v118, s[38:39]
	global_load_dwordx2 v[102:103], v118, s[18:19]
	global_load_dwordx2 v[106:107], v118, s[68:69]
	global_load_dwordx2 v[108:109], v118, s[56:57]
	global_load_dword v114, v121, s[38:39]
	global_load_dword v115, v121, s[18:19]
	s_add_i32 s20, s20, s22
	v_lshlrev_b32_e32 v44, 16, v28
	v_and_b32_e32 v45, 0xffff0000, v28
	v_lshlrev_b32_e32 v28, 16, v29
	v_and_b32_e32 v29, 0xffff0000, v29
	v_lshlrev_b32_e32 v46, 16, v30
	v_and_b32_e32 v47, 0xffff0000, v30
	v_lshlrev_b32_e32 v30, 16, v31
	v_and_b32_e32 v31, 0xffff0000, v31
	v_pk_add_f32 v[28:29], v[28:29], v[30:31]
	v_pk_add_f32 v[30:31], v[44:45], v[46:47]
	v_add_f32_e32 v0, v30, v31
	v_add_f32_e32 v0, v28, v0
	v_add_f32_e32 v0, v29, v0
	s_nop 1
	v_add_f32_dpp v0, v0, v0 quad_perm:[1,0,3,2] row_mask:0xf bank_mask:0xf bound_ctrl:1
	s_nop 0
	v_add_f32_dpp v0, v0, v0 quad_perm:[2,3,0,1] row_mask:0xf bank_mask:0xf bound_ctrl:1
	s_nop 1
	v_add_f32_dpp v0, v0, v0 row_half_mirror row_mask:0xf bank_mask:0xf bound_ctrl:1
	s_nop 1
	v_add_f32_dpp v0, v0, v0 row_ror:8 row_mask:0xf bank_mask:0xf bound_ctrl:1
	v_fmamk_f32 v31, v0, 0xbc800000, v31
	v_fmac_f32_e32 v30, 0xbc800000, v0
	v_fmamk_f32 v29, v0, 0xbc800000, v29
	v_fmac_f32_e32 v28, 0xbc800000, v0
	v_pk_mul_f32 v[18:19], v[30:31], v[30:31]
	v_pk_mul_f32 v[14:15], v[28:29], v[28:29]
	v_add_f32_e32 v5, v18, v19
	v_add_f32_e32 v5, v14, v5
	v_add_f32_e32 v5, v15, v5
	v_add_f32_e32 v0, v42, v43
	v_lshlrev_b32_e32 v50, 16, v34
	v_add_f32_dpp v5, v5, v5 quad_perm:[1,0,3,2] row_mask:0xf bank_mask:0xf bound_ctrl:1
	s_nop 0
	v_and_b32_e32 v51, 0xffff0000, v34
	v_add_f32_dpp v5, v5, v5 quad_perm:[2,3,0,1] row_mask:0xf bank_mask:0xf bound_ctrl:1
	s_nop 0
	v_lshlrev_b32_e32 v34, 16, v35
	v_add_f32_dpp v5, v5, v5 row_half_mirror row_mask:0xf bank_mask:0xf bound_ctrl:1
	s_nop 0
	v_and_b32_e32 v35, 0xffff0000, v35
	v_add_f32_dpp v5, v5, v5 row_ror:8 row_mask:0xf bank_mask:0xf bound_ctrl:1
	v_fmamk_f32 v5, v5, 0x3c800000, v3
	v_mul_f32_e32 v14, 0x4f800000, v5
	v_cmp_gt_f32_e32 vcc, s24, v5
	s_nop 0
	v_lshlrev_b32_e32 v52, 16, v36
	v_cndmask_b32_e32 v5, v5, v14, vcc
	v_sqrt_f32_e32 v14, v5
	v_and_b32_e32 v53, 0xffff0000, v36
	v_lshlrev_b32_e32 v36, 16, v37
	v_and_b32_e32 v37, 0xffff0000, v37
	v_add_u32_e32 v15, -1, v14
	v_add_u32_e32 v16, 1, v14
	v_fma_f32 v17, -v15, v14, v5
	v_fma_f32 v18, -v16, v14, v5
	v_cmp_ge_f32_e64 s[6:7], 0, v17
	s_nop 1
	v_cndmask_b32_e64 v14, v14, v15, s[6:7]
	v_cmp_lt_f32_e64 s[6:7], 0, v18
	s_nop 1
	v_cndmask_b32_e64 v14, v14, v16, s[6:7]
	v_mul_f32_e32 v15, 0x37800000, v14
	v_cndmask_b32_e32 v14, v14, v15, vcc
	v_cmp_class_f32_e32 vcc, v5, v4
	s_nop 1
	v_cndmask_b32_e32 v5, v14, v5, vcc
	v_div_scale_f32 v14, s[0:1], v5, v5, 1.0
	v_rcp_f32_e32 v16, v14
	v_div_scale_f32 v15, vcc, 1.0, v5, 1.0
	v_fma_f32 v17, -v14, v16, 1.0
	v_fmac_f32_e32 v16, v17, v16
	v_mul_f32_e32 v17, v15, v16
	v_fma_f32 v18, -v14, v17, v15
	v_fmac_f32_e32 v17, v18, v16
	v_fma_f32 v14, -v14, v17, v15
	v_div_fmas_f32 v14, v14, v16, v17
	v_div_fixup_f32 v14, v14, v5, 1.0
	v_pk_mul_f32 v[16:17], v[30:31], v[14:15] op_sel_hi:[1,0]
	v_pk_mul_f32 v[14:15], v[28:29], v[14:15] op_sel_hi:[1,0]
	v_pk_fma_f32 v[6:7], v[6:7], v[16:17], v[10:11]
	v_pk_fma_f32 v[8:9], v[8:9], v[14:15], v[12:13]
	v_pk_fma_f32 v[6:7], v[0:1], v[50:51], v[6:7] op_sel_hi:[0,1,1]
	v_pk_fma_f32 v[8:9], v[0:1], v[34:35], v[8:9] op_sel_hi:[0,1,1]
	v_pk_mul_f32 v[6:7], v[6:7], v[52:53]
	v_pk_mul_f32 v[8:9], v[8:9], v[36:37]
	s_nop 1
	v_cvt_pk_bf16_f32 v6, v6, v7
	s_nop 0
	s_nop 1
	v_cvt_pk_bf16_f32 v7, v8, v9
	global_store_dwordx2 v26, v[6:7], s[8:9]
	s_sub_u32 s4, s4, 1
	s_cmp_lg_u32 s4, 0
	s_cbranch_scc1 .Lp6_loop
